# base23 + D2 step-2 product: k=2,3 operand fragments read up front into dead quads (MFMA shadow), counted lgkmcnt
# speedup vs baseline: 1.0053x; 1.0007x over previous
; #define LAS __attribute__((address_space(3)))
; __device__ __forceinline__ f32x16 mma64(f32x16 acc, const LAS bf16* A, const LAS bf16* BT, int lane) {
;     const int r = lane & 31, h = lane >> 5;
;     const LAS bf16* ap = A + r * TS + 8 * h; const LAS bf16* bp = BT + r * TS + 8 * h;
; #pragma unroll
;     for (int ks = 0; ks < 4; ++ks) { const bf16x8 av = *(const LAS bf16x8*)(ap + ks * 16), bv = *(const LAS bf16x8*)(bp + ks * 16); acc = __builtin_amdgcn_mfma_f32_32x32x16_bf16(av, bv, acc, 0, 0, 0); }
;     return acc;
; __device__ __forceinline__ void phase_scan_chunk(const Args& a, LAS unsigned char* lds, const WCtx& w, int l) {
;     ...
;                 { f32x16 acc = zero16();
;                   if (wn >= wm) { const LAS bf16* Ap = (wm == 0 && wn == 0) ? TX + 32 * TS : TK + 32 * wm * TS; const LAS bf16* Bp = (wn == 0) ? TQ : TX;
;                       acc = mma64(acc, Ap, Bp, lane); }
.LBB0_1505:
	s_waitcnt lgkmcnt(0)
	s_barrier
	v_mov_b32_e32 v2, 0
	s_andn2_b64 vcc, exec, s[6:7]
	v_mov_b32_e32 v3, 0
	v_mov_b32_e32 v4, 0
	v_mov_b32_e32 v5, 0
	v_mov_b32_e32 v6, 0
	v_mov_b32_e32 v7, 0
	v_mov_b32_e32 v8, 0
	v_mov_b32_e32 v9, 0
	v_mov_b32_e32 v10, 0
	v_mov_b32_e32 v11, 0
	v_mov_b32_e32 v12, 0
	v_mov_b32_e32 v13, 0
	v_mov_b32_e32 v14, 0
	v_mov_b32_e32 v15, 0
	v_mov_b32_e32 v16, 0
	v_mov_b32_e32 v17, 0
	s_cbranch_vccnz .LBB0_1432
	ds_read_b128 v[2:5], v126
	ds_read_b128 v[6:9], v127
	ds_read_b128 v[18:21], v126 offset:32
	ds_read_b128 v[22:25], v127 offset:32
	ds_read_b128 v[224:227], v126 offset:64
	ds_read_b128 v[238:241], v127 offset:64
	ds_read_b128 v[242:245], v126 offset:96
	ds_read_b128 v[246:249], v127 offset:96
	s_waitcnt lgkmcnt(6)
	v_mfma_f32_32x32x16_bf16 v[2:17], v[2:5], v[6:9], 0
	s_waitcnt lgkmcnt(4)
	v_mfma_f32_32x32x16_bf16 v[2:17], v[18:21], v[22:25], v[2:17]
	s_waitcnt lgkmcnt(2)
	v_mfma_f32_32x32x16_bf16 v[2:17], v[224:227], v[238:241], v[2:17]
	s_waitcnt lgkmcnt(0)
	v_mfma_f32_32x32x16_bf16 v[2:17], v[242:245], v[246:249], v[2:17]
	s_branch .LBB0_1432

; #define LAS __attribute__((address_space(3)))
; __device__ __forceinline__ f32x16 mma64(f32x16 acc, const LAS bf16* A, const LAS bf16* BT, int lane) {
;     const int r = lane & 31, h = lane >> 5;
;     const LAS bf16* ap = A + r * TS + 8 * h; const LAS bf16* bp = BT + r * TS + 8 * h;
; #pragma unroll
;     for (int ks = 0; ks < 4; ++ks) { const bf16x8 av = *(const LAS bf16x8*)(ap + ks * 16), bv = *(const LAS bf16x8*)(bp + ks * 16); acc = __builtin_amdgcn_mfma_f32_32x32x16_bf16(av, bv, acc, 0, 0, 0); }
;     return acc;
; __device__ __forceinline__ void phase_scan_chunk(const Args& a, LAS unsigned char* lds, const WCtx& w, int l) {
;     ...
;                 { f32x16 acc = zero16();
;                   if (wn >= wm) acc = mma64(acc, TK + 32 * wm * TS, TQ + 32 * wn * TS, lane);
.LBB0_1558:
	s_waitcnt lgkmcnt(0)
	s_barrier
	v_cndmask_b32_e64 v3, 0, 1, s[92:93]
	v_mov_b32_e32 v2, 0
	v_cmp_ne_u32_e64 s[72:73], 1, v3
	s_andn2_b64 vcc, exec, s[92:93]
	v_mov_b32_e32 v3, 0
	v_mov_b32_e32 v4, 0
	v_mov_b32_e32 v5, 0
	v_mov_b32_e32 v6, 0
	v_mov_b32_e32 v7, 0
	v_mov_b32_e32 v8, 0
	v_mov_b32_e32 v9, 0
	v_mov_b32_e32 v10, 0
	v_mov_b32_e32 v11, 0
	v_mov_b32_e32 v12, 0
	v_mov_b32_e32 v13, 0
	v_mov_b32_e32 v14, 0
	v_mov_b32_e32 v15, 0
	v_mov_b32_e32 v16, 0
	v_mov_b32_e32 v17, 0
	s_cbranch_vccnz .LBB0_1560
	ds_read_b128 v[2:5], v174 offset:9216
	ds_read_b128 v[6:9], v175
	ds_read_b128 v[18:21], v174 offset:9248
	ds_read_b128 v[22:25], v175 offset:32
	ds_read_b128 v[224:227], v174 offset:9280
	ds_read_b128 v[238:241], v175 offset:64
	ds_read_b128 v[242:245], v174 offset:9312
	ds_read_b128 v[246:249], v175 offset:96
	s_waitcnt lgkmcnt(6)
	v_mfma_f32_32x32x16_bf16 v[2:17], v[2:5], v[6:9], 0
	s_waitcnt lgkmcnt(4)
	v_mfma_f32_32x32x16_bf16 v[2:17], v[18:21], v[22:25], v[2:17]
	s_waitcnt lgkmcnt(2)
	v_mfma_f32_32x32x16_bf16 v[2:17], v[224:227], v[238:241], v[2:17]
	s_waitcnt lgkmcnt(0)
	v_mfma_f32_32x32x16_bf16 v[2:17], v[242:245], v[246:249], v[2:17]

; #define LAS __attribute__((address_space(3)))
; __device__ __forceinline__ f32x16 mma64(f32x16 acc, const LAS bf16* A, const LAS bf16* BT, int lane) {
;     const int r = lane & 31, h = lane >> 5;
;     const LAS bf16* ap = A + r * TS + 8 * h; const LAS bf16* bp = BT + r * TS + 8 * h;
; #pragma unroll
;     for (int ks = 0; ks < 4; ++ks) { const bf16x8 av = *(const LAS bf16x8*)(ap + ks * 16), bv = *(const LAS bf16x8*)(bp + ks * 16); acc = __builtin_amdgcn_mfma_f32_32x32x16_bf16(av, bv, acc, 0, 0, 0); }
;     return acc;
; __device__ __forceinline__ void phase_scan_chunk(const Args& a, LAS unsigned char* lds, const WCtx& w, int l) {
;     ...
;                 { f32x16 acc = zero16();
;                   if (wn >= wm) acc = mma64(acc, TK + 32 * wm * TS, TQ + 32 * wn * TS, lane);
.LBB0_1584:
	s_waitcnt lgkmcnt(0)
	s_barrier
	v_mov_b32_e32 v2, 0
	s_and_b64 vcc, exec, s[72:73]
	v_mov_b32_e32 v3, 0
	v_mov_b32_e32 v4, 0
	v_mov_b32_e32 v5, 0
	v_mov_b32_e32 v6, 0
	v_mov_b32_e32 v7, 0
	v_mov_b32_e32 v8, 0
	v_mov_b32_e32 v9, 0
	v_mov_b32_e32 v10, 0
	v_mov_b32_e32 v11, 0
	v_mov_b32_e32 v12, 0
	v_mov_b32_e32 v13, 0
	v_mov_b32_e32 v14, 0
	v_mov_b32_e32 v15, 0
	v_mov_b32_e32 v16, 0
	v_mov_b32_e32 v17, 0
	s_cbranch_vccnz .LBB0_1586
	ds_read_b128 v[2:5], v174 offset:9216
	ds_read_b128 v[6:9], v175
	ds_read_b128 v[18:21], v174 offset:9248
	ds_read_b128 v[22:25], v175 offset:32
	ds_read_b128 v[224:227], v174 offset:9280
	ds_read_b128 v[238:241], v175 offset:64
	ds_read_b128 v[242:245], v174 offset:9312
	ds_read_b128 v[246:249], v175 offset:96
	s_waitcnt lgkmcnt(6)
	v_mfma_f32_32x32x16_bf16 v[2:17], v[2:5], v[6:9], 0
	s_waitcnt lgkmcnt(4)
	v_mfma_f32_32x32x16_bf16 v[2:17], v[18:21], v[22:25], v[2:17]
	s_waitcnt lgkmcnt(2)
	v_mfma_f32_32x32x16_bf16 v[2:17], v[224:227], v[238:241], v[2:17]
	s_waitcnt lgkmcnt(0)
	v_mfma_f32_32x32x16_bf16 v[2:17], v[242:245], v[246:249], v[2:17]
